# P1 epilogue rope (q/k tiles): per-element ds_bpermute + lgkmcnt(0) + exec-masked regions replaced by v_permlane16_swap pairs and selects, same separately-rounded x*cos -/+ other*sin
# speedup vs baseline: 1.0382x; 1.0197x over previous
;     DI void operator()(const pg8::f32x4 (&acc)[2][2][4][2], const pg8::Unit& u, int wr, int wc, int fr, int fq) const {
;     ...
;                     if (do_rope) {
;                         const f32x4* cs = (const f32x4*)(rope + (size_t)pos * 16);
;                         const f32x4 c01 = cs[0], c23 = cs[1], c45 = cs[2], c67 = cs[3];
;                         const float cc[8] = {c01.x, c01.z, c23.x, c23.z, c45.x, c45.z, c67.x, c67.z};
;                         const float sn[8] = {c01.y, c01.w, c23.y, c23.w, c45.y, c45.w, c67.y, c67.w};
; #pragma unroll
;                         for (int j = 0; j < 8; ++j) {
;                             const float other = __shfl_xor(v[j], 16);
;                             const float r0 = v[j] * cc[j] - other * sn[j], r1 = v[j] * cc[j] + other * sn[j];
;                             v[j] = fq == 0 ? r0 : (fq == 1 ? r1 : v[j]);
;                         }
;                     }
.LBB0_301:
	v_bitop3_b32 v182, s74, v177, v167 bitop3:0xc8
	v_lshlrev_b32_e32 v152, 6, v182
	v_lshl_add_u64 v[136:137], s[70:71], 0, v[152:153]
	s_andn2_b64 vcc, exec, s[4:5]
	v_lshl_add_u64 v[160:161], v[136:137], 0, s[34:35]
	s_cbranch_vccnz .LBB0_351
	global_load_dwordx4 v[140:143], v[160:161], off offset:16
	global_load_dwordx4 v[0:3], v[160:161], off
	global_load_dwordx4 v[136:139], v[160:161], off offset:48
	global_load_dwordx4 v[4:7], v[160:161], off offset:32
	v_and_b32_e32 v237, 1, v168
	v_cmp_eq_u32_e64 s[4:5], 1, v237
	v_cmp_gt_u32_e64 s[78:79], 2, v168
	v_cmp_eq_u32_e32 vcc, 0, v168
	v_bfrev_b32_e32 v239, 1
	v_cndmask_b32_e32 v238, 0, v239, vcc
	v_mov_b32_e32 v248, v8
	v_mov_b32_e32 v252, v8
	v_mov_b32_e32 v249, v9
	v_mov_b32_e32 v253, v9
	v_mov_b32_e32 v250, v10
	v_mov_b32_e32 v254, v10
	v_mov_b32_e32 v251, v11
	v_mov_b32_e32 v255, v11
	v_permlane16_swap_b32_e32 v248, v252
	v_permlane16_swap_b32_e32 v249, v253
	v_permlane16_swap_b32_e32 v250, v254
	v_permlane16_swap_b32_e32 v251, v255
	s_nop 1
	v_cndmask_b32_e64 v248, v252, v248, s[4:5]
	v_cndmask_b32_e64 v249, v253, v249, s[4:5]
	v_cndmask_b32_e64 v250, v254, v250, s[4:5]
	v_cndmask_b32_e64 v251, v255, v251, s[4:5]
	s_waitcnt vmcnt(0)
	v_mul_f32_e32 v252, v8, v0
	v_xor_b32_e32 v237, v238, v1
	v_mul_f32_e32 v248, v248, v237
	v_add_f32_e32 v248, v252, v248
	v_cndmask_b32_e64 v8, v8, v248, s[78:79]
	v_mul_f32_e32 v253, v9, v2
	v_xor_b32_e32 v237, v238, v3
	v_mul_f32_e32 v249, v249, v237
	v_add_f32_e32 v249, v253, v249
	v_cndmask_b32_e64 v9, v9, v249, s[78:79]
	v_mul_f32_e32 v254, v10, v140
	v_xor_b32_e32 v237, v238, v141
	v_mul_f32_e32 v250, v250, v237
	v_add_f32_e32 v250, v254, v250
	v_cndmask_b32_e64 v10, v10, v250, s[78:79]
	v_mul_f32_e32 v255, v11, v142
	v_xor_b32_e32 v237, v238, v143
	v_mul_f32_e32 v251, v251, v237
	v_add_f32_e32 v251, v255, v251
	v_cndmask_b32_e64 v11, v11, v251, s[78:79]
	v_mov_b32_e32 v248, v12
	v_mov_b32_e32 v252, v12
	v_mov_b32_e32 v249, v13
	v_mov_b32_e32 v253, v13
	v_mov_b32_e32 v250, v14
	v_mov_b32_e32 v254, v14
	v_mov_b32_e32 v251, v15
	v_mov_b32_e32 v255, v15
	v_permlane16_swap_b32_e32 v248, v252
	v_permlane16_swap_b32_e32 v249, v253
	v_permlane16_swap_b32_e32 v250, v254
	v_permlane16_swap_b32_e32 v251, v255
	s_nop 1
	v_cndmask_b32_e64 v248, v252, v248, s[4:5]
	v_cndmask_b32_e64 v249, v253, v249, s[4:5]
	v_cndmask_b32_e64 v250, v254, v250, s[4:5]
	v_cndmask_b32_e64 v251, v255, v251, s[4:5]
	v_mul_f32_e32 v252, v12, v4
	v_xor_b32_e32 v237, v238, v5
	v_mul_f32_e32 v248, v248, v237
	v_add_f32_e32 v248, v252, v248
	v_cndmask_b32_e64 v12, v12, v248, s[78:79]
	v_mul_f32_e32 v253, v13, v6
	v_xor_b32_e32 v237, v238, v7
	v_mul_f32_e32 v249, v249, v237
	v_add_f32_e32 v249, v253, v249
	v_cndmask_b32_e64 v13, v13, v249, s[78:79]
	v_mul_f32_e32 v254, v14, v136
	v_xor_b32_e32 v237, v238, v137
	v_mul_f32_e32 v250, v250, v237
	v_add_f32_e32 v250, v254, v250
	v_cndmask_b32_e64 v14, v14, v250, s[78:79]
	v_mul_f32_e32 v255, v15, v138
	v_xor_b32_e32 v237, v238, v139
	v_mul_f32_e32 v251, v251, v237
	v_add_f32_e32 v251, v255, v251
	v_cndmask_b32_e64 v15, v15, v251, s[78:79]
	v_mov_b64_e32 v[0:1], v[8:9]
	v_mov_b64_e32 v[2:3], v[10:11]
	v_mov_b64_e32 v[4:5], v[12:13]
	v_mov_b64_e32 v[6:7], v[14:15]

;     DI void operator()(const pg8::f32x4 (&acc)[2][2][4][2], const pg8::Unit& u, int wr, int wc, int fr, int fq) const {
;     ...
;                     if (do_rope) {
;                         const f32x4* cs = (const f32x4*)(rope + (size_t)pos * 16);
;                         const f32x4 c01 = cs[0], c23 = cs[1], c45 = cs[2], c67 = cs[3];
;                         const float cc[8] = {c01.x, c01.z, c23.x, c23.z, c45.x, c45.z, c67.x, c67.z};
;                         const float sn[8] = {c01.y, c01.w, c23.y, c23.w, c45.y, c45.w, c67.y, c67.w};
; #pragma unroll
;                         for (int j = 0; j < 8; ++j) {
;                             const float other = __shfl_xor(v[j], 16);
;                             const float r0 = v[j] * cc[j] - other * sn[j], r1 = v[j] * cc[j] + other * sn[j];
;                             v[j] = fq == 0 ? r0 : (fq == 1 ? r1 : v[j]);
;                         }
;                     }
.LBB0_373:
	s_andn2_b64 vcc, exec, s[8:9]
	s_cbranch_vccnz .LBB0_423
	global_load_dwordx4 v[132:135], v[160:161], off offset:16
	global_load_dwordx4 v[0:3], v[160:161], off
	global_load_dwordx4 v[128:131], v[160:161], off offset:48
	global_load_dwordx4 v[4:7], v[160:161], off offset:32
	v_and_b32_e32 v237, 1, v168
	v_cmp_eq_u32_e64 s[8:9], 1, v237
	v_cmp_gt_u32_e64 s[76:77], 2, v168
	v_cmp_eq_u32_e32 vcc, 0, v168
	v_bfrev_b32_e32 v239, 1
	v_cndmask_b32_e32 v238, 0, v239, vcc
	v_mov_b32_e32 v248, v8
	v_mov_b32_e32 v252, v8
	v_mov_b32_e32 v249, v9
	v_mov_b32_e32 v253, v9
	v_mov_b32_e32 v250, v10
	v_mov_b32_e32 v254, v10
	v_mov_b32_e32 v251, v11
	v_mov_b32_e32 v255, v11
	v_permlane16_swap_b32_e32 v248, v252
	v_permlane16_swap_b32_e32 v249, v253
	v_permlane16_swap_b32_e32 v250, v254
	v_permlane16_swap_b32_e32 v251, v255
	s_nop 1
	v_cndmask_b32_e64 v248, v252, v248, s[8:9]
	v_cndmask_b32_e64 v249, v253, v249, s[8:9]
	v_cndmask_b32_e64 v250, v254, v250, s[8:9]
	v_cndmask_b32_e64 v251, v255, v251, s[8:9]
	s_waitcnt vmcnt(0)
	v_mul_f32_e32 v252, v8, v0
	v_xor_b32_e32 v237, v238, v1
	v_mul_f32_e32 v248, v248, v237
	v_add_f32_e32 v248, v252, v248
	v_cndmask_b32_e64 v8, v8, v248, s[76:77]
	v_mul_f32_e32 v253, v9, v2
	v_xor_b32_e32 v237, v238, v3
	v_mul_f32_e32 v249, v249, v237
	v_add_f32_e32 v249, v253, v249
	v_cndmask_b32_e64 v9, v9, v249, s[76:77]
	v_mul_f32_e32 v254, v10, v132
	v_xor_b32_e32 v237, v238, v133
	v_mul_f32_e32 v250, v250, v237
	v_add_f32_e32 v250, v254, v250
	v_cndmask_b32_e64 v10, v10, v250, s[76:77]
	v_mul_f32_e32 v255, v11, v134
	v_xor_b32_e32 v237, v238, v135
	v_mul_f32_e32 v251, v251, v237
	v_add_f32_e32 v251, v255, v251
	v_cndmask_b32_e64 v11, v11, v251, s[76:77]
	v_mov_b32_e32 v248, v12
	v_mov_b32_e32 v252, v12
	v_mov_b32_e32 v249, v13
	v_mov_b32_e32 v253, v13
	v_mov_b32_e32 v250, v14
	v_mov_b32_e32 v254, v14
	v_mov_b32_e32 v251, v15
	v_mov_b32_e32 v255, v15
	v_permlane16_swap_b32_e32 v248, v252
	v_permlane16_swap_b32_e32 v249, v253
	v_permlane16_swap_b32_e32 v250, v254
	v_permlane16_swap_b32_e32 v251, v255
	s_nop 1
	v_cndmask_b32_e64 v248, v252, v248, s[8:9]
	v_cndmask_b32_e64 v249, v253, v249, s[8:9]
	v_cndmask_b32_e64 v250, v254, v250, s[8:9]
	v_cndmask_b32_e64 v251, v255, v251, s[8:9]
	v_mul_f32_e32 v252, v12, v4
	v_xor_b32_e32 v237, v238, v5
	v_mul_f32_e32 v248, v248, v237
	v_add_f32_e32 v248, v252, v248
	v_cndmask_b32_e64 v12, v12, v248, s[76:77]
	v_mul_f32_e32 v253, v13, v6
	v_xor_b32_e32 v237, v238, v7
	v_mul_f32_e32 v249, v249, v237
	v_add_f32_e32 v249, v253, v249
	v_cndmask_b32_e64 v13, v13, v249, s[76:77]
	v_mul_f32_e32 v254, v14, v128
	v_xor_b32_e32 v237, v238, v129
	v_mul_f32_e32 v250, v250, v237
	v_add_f32_e32 v250, v254, v250
	v_cndmask_b32_e64 v14, v14, v250, s[76:77]
	v_mul_f32_e32 v255, v15, v130
	v_xor_b32_e32 v237, v238, v131
	v_mul_f32_e32 v251, v251, v237
	v_add_f32_e32 v251, v255, v251
	v_cndmask_b32_e64 v15, v15, v251, s[76:77]
	v_mov_b64_e32 v[0:1], v[8:9]
	v_mov_b64_e32 v[2:3], v[10:11]
	v_mov_b64_e32 v[4:5], v[12:13]
	v_mov_b64_e32 v[6:7], v[14:15]

;     DI void operator()(const pg8::f32x4 (&acc)[2][2][4][2], const pg8::Unit& u, int wr, int wc, int fr, int fq) const {
;     ...
;                     if (do_rope) {
;                         const f32x4* cs = (const f32x4*)(rope + (size_t)pos * 16);
;                         const f32x4 c01 = cs[0], c23 = cs[1], c45 = cs[2], c67 = cs[3];
;                         const float cc[8] = {c01.x, c01.z, c23.x, c23.z, c45.x, c45.z, c67.x, c67.z};
;                         const float sn[8] = {c01.y, c01.w, c23.y, c23.w, c45.y, c45.w, c67.y, c67.w};
; #pragma unroll
;                         for (int j = 0; j < 8; ++j) {
;                             const float other = __shfl_xor(v[j], 16);
;                             const float r0 = v[j] * cc[j] - other * sn[j], r1 = v[j] * cc[j] + other * sn[j];
;                             v[j] = fq == 0 ? r0 : (fq == 1 ? r1 : v[j]);
;                         }
;                     }
.LBB0_445:
	v_bitop3_b32 v129, s74, v179, v171 bitop3:0xc8
	v_lshlrev_b32_e32 v152, 6, v129
	v_lshl_add_u64 v[120:121], s[70:71], 0, v[152:153]
	s_andn2_b64 vcc, exec, s[58:59]
	v_lshl_add_u64 v[132:133], v[120:121], 0, s[34:35]
	s_cbranch_vccnz .LBB0_495
	global_load_dwordx4 v[124:127], v[132:133], off offset:16
	global_load_dwordx4 v[0:3], v[132:133], off
	global_load_dwordx4 v[120:123], v[132:133], off offset:48
	global_load_dwordx4 v[4:7], v[132:133], off offset:32
	v_and_b32_e32 v237, 1, v168
	v_cmp_eq_u32_e64 s[52:53], 1, v237
	v_cmp_gt_u32_e64 s[58:59], 2, v168
	v_cmp_eq_u32_e32 vcc, 0, v168
	v_bfrev_b32_e32 v239, 1
	v_cndmask_b32_e32 v238, 0, v239, vcc
	v_mov_b32_e32 v248, v8
	v_mov_b32_e32 v252, v8
	v_mov_b32_e32 v249, v9
	v_mov_b32_e32 v253, v9
	v_mov_b32_e32 v250, v10
	v_mov_b32_e32 v254, v10
	v_mov_b32_e32 v251, v11
	v_mov_b32_e32 v255, v11
	v_permlane16_swap_b32_e32 v248, v252
	v_permlane16_swap_b32_e32 v249, v253
	v_permlane16_swap_b32_e32 v250, v254
	v_permlane16_swap_b32_e32 v251, v255
	s_nop 1
	v_cndmask_b32_e64 v248, v252, v248, s[52:53]
	v_cndmask_b32_e64 v249, v253, v249, s[52:53]
	v_cndmask_b32_e64 v250, v254, v250, s[52:53]
	v_cndmask_b32_e64 v251, v255, v251, s[52:53]
	s_waitcnt vmcnt(0)
	v_mul_f32_e32 v252, v8, v0
	v_xor_b32_e32 v237, v238, v1
	v_mul_f32_e32 v248, v248, v237
	v_add_f32_e32 v248, v252, v248
	v_cndmask_b32_e64 v8, v8, v248, s[58:59]
	v_mul_f32_e32 v253, v9, v2
	v_xor_b32_e32 v237, v238, v3
	v_mul_f32_e32 v249, v249, v237
	v_add_f32_e32 v249, v253, v249
	v_cndmask_b32_e64 v9, v9, v249, s[58:59]
	v_mul_f32_e32 v254, v10, v124
	v_xor_b32_e32 v237, v238, v125
	v_mul_f32_e32 v250, v250, v237
	v_add_f32_e32 v250, v254, v250
	v_cndmask_b32_e64 v10, v10, v250, s[58:59]
	v_mul_f32_e32 v255, v11, v126
	v_xor_b32_e32 v237, v238, v127
	v_mul_f32_e32 v251, v251, v237
	v_add_f32_e32 v251, v255, v251
	v_cndmask_b32_e64 v11, v11, v251, s[58:59]
	v_mov_b32_e32 v248, v12
	v_mov_b32_e32 v252, v12
	v_mov_b32_e32 v249, v13
	v_mov_b32_e32 v253, v13
	v_mov_b32_e32 v250, v14
	v_mov_b32_e32 v254, v14
	v_mov_b32_e32 v251, v15
	v_mov_b32_e32 v255, v15
	v_permlane16_swap_b32_e32 v248, v252
	v_permlane16_swap_b32_e32 v249, v253
	v_permlane16_swap_b32_e32 v250, v254
	v_permlane16_swap_b32_e32 v251, v255
	s_nop 1
	v_cndmask_b32_e64 v248, v252, v248, s[52:53]
	v_cndmask_b32_e64 v249, v253, v249, s[52:53]
	v_cndmask_b32_e64 v250, v254, v250, s[52:53]
	v_cndmask_b32_e64 v251, v255, v251, s[52:53]
	v_mul_f32_e32 v252, v12, v4
	v_xor_b32_e32 v237, v238, v5
	v_mul_f32_e32 v248, v248, v237
	v_add_f32_e32 v248, v252, v248
	v_cndmask_b32_e64 v12, v12, v248, s[58:59]
	v_mul_f32_e32 v253, v13, v6
	v_xor_b32_e32 v237, v238, v7
	v_mul_f32_e32 v249, v249, v237
	v_add_f32_e32 v249, v253, v249
	v_cndmask_b32_e64 v13, v13, v249, s[58:59]
	v_mul_f32_e32 v254, v14, v120
	v_xor_b32_e32 v237, v238, v121
	v_mul_f32_e32 v250, v250, v237
	v_add_f32_e32 v250, v254, v250
	v_cndmask_b32_e64 v14, v14, v250, s[58:59]
	v_mul_f32_e32 v255, v15, v122
	v_xor_b32_e32 v237, v238, v123
	v_mul_f32_e32 v251, v251, v237
	v_add_f32_e32 v251, v255, v251
	v_cndmask_b32_e64 v15, v15, v251, s[58:59]
	v_mov_b64_e32 v[0:1], v[8:9]
	v_mov_b64_e32 v[2:3], v[10:11]
	v_mov_b64_e32 v[4:5], v[12:13]
	v_mov_b64_e32 v[6:7], v[14:15]

;     DI void operator()(const pg8::f32x4 (&acc)[2][2][4][2], const pg8::Unit& u, int wr, int wc, int fr, int fq) const {
;     ...
;                     if (do_rope) {
;                         const f32x4* cs = (const f32x4*)(rope + (size_t)pos * 16);
;                         const f32x4 c01 = cs[0], c23 = cs[1], c45 = cs[2], c67 = cs[3];
;                         const float cc[8] = {c01.x, c01.z, c23.x, c23.z, c45.x, c45.z, c67.x, c67.z};
;                         const float sn[8] = {c01.y, c01.w, c23.y, c23.w, c45.y, c45.w, c67.y, c67.w};
; #pragma unroll
;                         for (int j = 0; j < 8; ++j) {
;                             const float other = __shfl_xor(v[j], 16);
;                             const float r0 = v[j] * cc[j] - other * sn[j], r1 = v[j] * cc[j] + other * sn[j];
;                             v[j] = fq == 0 ? r0 : (fq == 1 ? r1 : v[j]);
;                         }
;                     }
.LBB0_526:
	global_load_dwordx4 v[116:119], v[132:133], off offset:16
	global_load_dwordx4 v[0:3], v[132:133], off
	global_load_dwordx4 v[112:115], v[132:133], off offset:48
	global_load_dwordx4 v[4:7], v[132:133], off offset:32
	v_and_b32_e32 v237, 1, v168
	v_cmp_eq_u32_e64 s[52:53], 1, v237
	v_cmp_gt_u32_e64 s[58:59], 2, v168
	v_cmp_eq_u32_e32 vcc, 0, v168
	v_bfrev_b32_e32 v239, 1
	v_cndmask_b32_e32 v238, 0, v239, vcc
	v_mov_b32_e32 v248, v8
	v_mov_b32_e32 v252, v8
	v_mov_b32_e32 v249, v9
	v_mov_b32_e32 v253, v9
	v_mov_b32_e32 v250, v10
	v_mov_b32_e32 v254, v10
	v_mov_b32_e32 v251, v11
	v_mov_b32_e32 v255, v11
	v_permlane16_swap_b32_e32 v248, v252
	v_permlane16_swap_b32_e32 v249, v253
	v_permlane16_swap_b32_e32 v250, v254
	v_permlane16_swap_b32_e32 v251, v255
	s_nop 1
	v_cndmask_b32_e64 v248, v252, v248, s[52:53]
	v_cndmask_b32_e64 v249, v253, v249, s[52:53]
	v_cndmask_b32_e64 v250, v254, v250, s[52:53]
	v_cndmask_b32_e64 v251, v255, v251, s[52:53]
	s_waitcnt vmcnt(0)
	v_mul_f32_e32 v252, v8, v0
	v_xor_b32_e32 v237, v238, v1
	v_mul_f32_e32 v248, v248, v237
	v_add_f32_e32 v248, v252, v248
	v_cndmask_b32_e64 v8, v8, v248, s[58:59]
	v_mul_f32_e32 v253, v9, v2
	v_xor_b32_e32 v237, v238, v3
	v_mul_f32_e32 v249, v249, v237
	v_add_f32_e32 v249, v253, v249
	v_cndmask_b32_e64 v9, v9, v249, s[58:59]
	v_mul_f32_e32 v254, v10, v116
	v_xor_b32_e32 v237, v238, v117
	v_mul_f32_e32 v250, v250, v237
	v_add_f32_e32 v250, v254, v250
	v_cndmask_b32_e64 v10, v10, v250, s[58:59]
	v_mul_f32_e32 v255, v11, v118
	v_xor_b32_e32 v237, v238, v119
	v_mul_f32_e32 v251, v251, v237
	v_add_f32_e32 v251, v255, v251
	v_cndmask_b32_e64 v11, v11, v251, s[58:59]
	v_mov_b32_e32 v248, v12
	v_mov_b32_e32 v252, v12
	v_mov_b32_e32 v249, v13
	v_mov_b32_e32 v253, v13
	v_mov_b32_e32 v250, v14
	v_mov_b32_e32 v254, v14
	v_mov_b32_e32 v251, v15
	v_mov_b32_e32 v255, v15
	v_permlane16_swap_b32_e32 v248, v252
	v_permlane16_swap_b32_e32 v249, v253
	v_permlane16_swap_b32_e32 v250, v254
	v_permlane16_swap_b32_e32 v251, v255
	s_nop 1
	v_cndmask_b32_e64 v248, v252, v248, s[52:53]
	v_cndmask_b32_e64 v249, v253, v249, s[52:53]
	v_cndmask_b32_e64 v250, v254, v250, s[52:53]
	v_cndmask_b32_e64 v251, v255, v251, s[52:53]
	v_mul_f32_e32 v252, v12, v4
	v_xor_b32_e32 v237, v238, v5
	v_mul_f32_e32 v248, v248, v237
	v_add_f32_e32 v248, v252, v248
	v_cndmask_b32_e64 v12, v12, v248, s[58:59]
	v_mul_f32_e32 v253, v13, v6
	v_xor_b32_e32 v237, v238, v7
	v_mul_f32_e32 v249, v249, v237
	v_add_f32_e32 v249, v253, v249
	v_cndmask_b32_e64 v13, v13, v249, s[58:59]
	v_mul_f32_e32 v254, v14, v112
	v_xor_b32_e32 v237, v238, v113
	v_mul_f32_e32 v250, v250, v237
	v_add_f32_e32 v250, v254, v250
	v_cndmask_b32_e64 v14, v14, v250, s[58:59]
	v_mul_f32_e32 v255, v15, v114
	v_xor_b32_e32 v237, v238, v115
	v_mul_f32_e32 v251, v251, v237
	v_add_f32_e32 v251, v255, v251
	v_cndmask_b32_e64 v15, v15, v251, s[58:59]
	v_mov_b64_e32 v[0:1], v[8:9]
	v_mov_b64_e32 v[2:3], v[10:11]
	v_mov_b64_e32 v[4:5], v[12:13]
	v_mov_b64_e32 v[6:7], v[14:15]
	s_and_b64 vcc, exec, s[8:9]
	s_mov_b64 s[58:59], -1
	s_cbranch_vccz .LBB0_518

;     DI void operator()(const pg8::f32x4 (&acc)[2][2][4][2], const pg8::Unit& u, int wr, int wc, int fr, int fq) const {
;     ...
;                     if (do_rope) {
;                         const f32x4* cs = (const f32x4*)(rope + (size_t)pos * 16);
;                         const f32x4 c01 = cs[0], c23 = cs[1], c45 = cs[2], c67 = cs[3];
;                         const float cc[8] = {c01.x, c01.z, c23.x, c23.z, c45.x, c45.z, c67.x, c67.z};
;                         const float sn[8] = {c01.y, c01.w, c23.y, c23.w, c45.y, c45.w, c67.y, c67.w};
; #pragma unroll
;                         for (int j = 0; j < 8; ++j) {
;                             const float other = __shfl_xor(v[j], 16);
;                             const float r0 = v[j] * cc[j] - other * sn[j], r1 = v[j] * cc[j] + other * sn[j];
;                             v[j] = fq == 0 ? r0 : (fq == 1 ? r1 : v[j]);
;                         }
;                     }
.LBB0_579:
	v_bitop3_b32 v120, s74, v180, v172 bitop3:0xc8
	v_lshlrev_b32_e32 v152, 6, v120
	v_lshl_add_u64 v[104:105], s[70:71], 0, v[152:153]
	s_andn2_b64 vcc, exec, s[58:59]
	v_lshl_add_u64 v[114:115], v[104:105], 0, s[34:35]
	s_cbranch_vccnz .LBB0_629
	global_load_dwordx4 v[108:111], v[114:115], off offset:16
	global_load_dwordx4 v[0:3], v[114:115], off
	global_load_dwordx4 v[104:107], v[114:115], off offset:48
	global_load_dwordx4 v[4:7], v[114:115], off offset:32
	v_and_b32_e32 v237, 1, v168
	v_cmp_eq_u32_e64 s[52:53], 1, v237
	v_cmp_gt_u32_e64 s[58:59], 2, v168
	v_cmp_eq_u32_e32 vcc, 0, v168
	v_bfrev_b32_e32 v239, 1
	v_cndmask_b32_e32 v238, 0, v239, vcc
	v_mov_b32_e32 v248, v8
	v_mov_b32_e32 v252, v8
	v_mov_b32_e32 v249, v9
	v_mov_b32_e32 v253, v9
	v_mov_b32_e32 v250, v10
	v_mov_b32_e32 v254, v10
	v_mov_b32_e32 v251, v11
	v_mov_b32_e32 v255, v11
	v_permlane16_swap_b32_e32 v248, v252
	v_permlane16_swap_b32_e32 v249, v253
	v_permlane16_swap_b32_e32 v250, v254
	v_permlane16_swap_b32_e32 v251, v255
	s_nop 1
	v_cndmask_b32_e64 v248, v252, v248, s[52:53]
	v_cndmask_b32_e64 v249, v253, v249, s[52:53]
	v_cndmask_b32_e64 v250, v254, v250, s[52:53]
	v_cndmask_b32_e64 v251, v255, v251, s[52:53]
	s_waitcnt vmcnt(0)
	v_mul_f32_e32 v252, v8, v0
	v_xor_b32_e32 v237, v238, v1
	v_mul_f32_e32 v248, v248, v237
	v_add_f32_e32 v248, v252, v248
	v_cndmask_b32_e64 v8, v8, v248, s[58:59]
	v_mul_f32_e32 v253, v9, v2
	v_xor_b32_e32 v237, v238, v3
	v_mul_f32_e32 v249, v249, v237
	v_add_f32_e32 v249, v253, v249
	v_cndmask_b32_e64 v9, v9, v249, s[58:59]
	v_mul_f32_e32 v254, v10, v108
	v_xor_b32_e32 v237, v238, v109
	v_mul_f32_e32 v250, v250, v237
	v_add_f32_e32 v250, v254, v250
	v_cndmask_b32_e64 v10, v10, v250, s[58:59]
	v_mul_f32_e32 v255, v11, v110
	v_xor_b32_e32 v237, v238, v111
	v_mul_f32_e32 v251, v251, v237
	v_add_f32_e32 v251, v255, v251
	v_cndmask_b32_e64 v11, v11, v251, s[58:59]
	v_mov_b32_e32 v248, v12
	v_mov_b32_e32 v252, v12
	v_mov_b32_e32 v249, v13
	v_mov_b32_e32 v253, v13
	v_mov_b32_e32 v250, v14
	v_mov_b32_e32 v254, v14
	v_mov_b32_e32 v251, v15
	v_mov_b32_e32 v255, v15
	v_permlane16_swap_b32_e32 v248, v252
	v_permlane16_swap_b32_e32 v249, v253
	v_permlane16_swap_b32_e32 v250, v254
	v_permlane16_swap_b32_e32 v251, v255
	s_nop 1
	v_cndmask_b32_e64 v248, v252, v248, s[52:53]
	v_cndmask_b32_e64 v249, v253, v249, s[52:53]
	v_cndmask_b32_e64 v250, v254, v250, s[52:53]
	v_cndmask_b32_e64 v251, v255, v251, s[52:53]
	v_mul_f32_e32 v252, v12, v4
	v_xor_b32_e32 v237, v238, v5
	v_mul_f32_e32 v248, v248, v237
	v_add_f32_e32 v248, v252, v248
	v_cndmask_b32_e64 v12, v12, v248, s[58:59]
	v_mul_f32_e32 v253, v13, v6
	v_xor_b32_e32 v237, v238, v7
	v_mul_f32_e32 v249, v249, v237
	v_add_f32_e32 v249, v253, v249
	v_cndmask_b32_e64 v13, v13, v249, s[58:59]
	v_mul_f32_e32 v254, v14, v104
	v_xor_b32_e32 v237, v238, v105
	v_mul_f32_e32 v250, v250, v237
	v_add_f32_e32 v250, v254, v250
	v_cndmask_b32_e64 v14, v14, v250, s[58:59]
	v_mul_f32_e32 v255, v15, v106
	v_xor_b32_e32 v237, v238, v107
	v_mul_f32_e32 v251, v251, v237
	v_add_f32_e32 v251, v255, v251
	v_cndmask_b32_e64 v15, v15, v251, s[58:59]
	v_mov_b64_e32 v[0:1], v[8:9]
	v_mov_b64_e32 v[2:3], v[10:11]
	v_mov_b64_e32 v[4:5], v[12:13]
	v_mov_b64_e32 v[6:7], v[14:15]

;     DI void operator()(const pg8::f32x4 (&acc)[2][2][4][2], const pg8::Unit& u, int wr, int wc, int fr, int fq) const {
;     ...
;                     if (do_rope) {
;                         const f32x4* cs = (const f32x4*)(rope + (size_t)pos * 16);
;                         const f32x4 c01 = cs[0], c23 = cs[1], c45 = cs[2], c67 = cs[3];
;                         const float cc[8] = {c01.x, c01.z, c23.x, c23.z, c45.x, c45.z, c67.x, c67.z};
;                         const float sn[8] = {c01.y, c01.w, c23.y, c23.w, c45.y, c45.w, c67.y, c67.w};
; #pragma unroll
;                         for (int j = 0; j < 8; ++j) {
;                             const float other = __shfl_xor(v[j], 16);
;                             const float r0 = v[j] * cc[j] - other * sn[j], r1 = v[j] * cc[j] + other * sn[j];
;                             v[j] = fq == 0 ? r0 : (fq == 1 ? r1 : v[j]);
;                         }
;                     }
.LBB0_670:
	global_load_dwordx4 v[100:103], v[114:115], off offset:16
	global_load_dwordx4 v[0:3], v[114:115], off
	global_load_dwordx4 v[96:99], v[114:115], off offset:48
	global_load_dwordx4 v[4:7], v[114:115], off offset:32
	v_and_b32_e32 v237, 1, v168
	v_cmp_eq_u32_e64 s[52:53], 1, v237
	v_cmp_gt_u32_e64 s[58:59], 2, v168
	v_cmp_eq_u32_e32 vcc, 0, v168
	v_bfrev_b32_e32 v239, 1
	v_cndmask_b32_e32 v238, 0, v239, vcc
	v_mov_b32_e32 v248, v8
	v_mov_b32_e32 v252, v8
	v_mov_b32_e32 v249, v9
	v_mov_b32_e32 v253, v9
	v_mov_b32_e32 v250, v10
	v_mov_b32_e32 v254, v10
	v_mov_b32_e32 v251, v11
	v_mov_b32_e32 v255, v11
	v_permlane16_swap_b32_e32 v248, v252
	v_permlane16_swap_b32_e32 v249, v253
	v_permlane16_swap_b32_e32 v250, v254
	v_permlane16_swap_b32_e32 v251, v255
	s_nop 1
	v_cndmask_b32_e64 v248, v252, v248, s[52:53]
	v_cndmask_b32_e64 v249, v253, v249, s[52:53]
	v_cndmask_b32_e64 v250, v254, v250, s[52:53]
	v_cndmask_b32_e64 v251, v255, v251, s[52:53]
	s_waitcnt vmcnt(0)
	v_mul_f32_e32 v252, v8, v0
	v_xor_b32_e32 v237, v238, v1
	v_mul_f32_e32 v248, v248, v237
	v_add_f32_e32 v248, v252, v248
	v_cndmask_b32_e64 v8, v8, v248, s[58:59]
	v_mul_f32_e32 v253, v9, v2
	v_xor_b32_e32 v237, v238, v3
	v_mul_f32_e32 v249, v249, v237
	v_add_f32_e32 v249, v253, v249
	v_cndmask_b32_e64 v9, v9, v249, s[58:59]
	v_mul_f32_e32 v254, v10, v100
	v_xor_b32_e32 v237, v238, v101
	v_mul_f32_e32 v250, v250, v237
	v_add_f32_e32 v250, v254, v250
	v_cndmask_b32_e64 v10, v10, v250, s[58:59]
	v_mul_f32_e32 v255, v11, v102
	v_xor_b32_e32 v237, v238, v103
	v_mul_f32_e32 v251, v251, v237
	v_add_f32_e32 v251, v255, v251
	v_cndmask_b32_e64 v11, v11, v251, s[58:59]
	v_mov_b32_e32 v248, v12
	v_mov_b32_e32 v252, v12
	v_mov_b32_e32 v249, v13
	v_mov_b32_e32 v253, v13
	v_mov_b32_e32 v250, v14
	v_mov_b32_e32 v254, v14
	v_mov_b32_e32 v251, v15
	v_mov_b32_e32 v255, v15
	v_permlane16_swap_b32_e32 v248, v252
	v_permlane16_swap_b32_e32 v249, v253
	v_permlane16_swap_b32_e32 v250, v254
	v_permlane16_swap_b32_e32 v251, v255
	s_nop 1
	v_cndmask_b32_e64 v248, v252, v248, s[52:53]
	v_cndmask_b32_e64 v249, v253, v249, s[52:53]
	v_cndmask_b32_e64 v250, v254, v250, s[52:53]
	v_cndmask_b32_e64 v251, v255, v251, s[52:53]
	v_mul_f32_e32 v252, v12, v4
	v_xor_b32_e32 v237, v238, v5
	v_mul_f32_e32 v248, v248, v237
	v_add_f32_e32 v248, v252, v248
	v_cndmask_b32_e64 v12, v12, v248, s[58:59]
	v_mul_f32_e32 v253, v13, v6
	v_xor_b32_e32 v237, v238, v7
	v_mul_f32_e32 v249, v249, v237
	v_add_f32_e32 v249, v253, v249
	v_cndmask_b32_e64 v13, v13, v249, s[58:59]
	v_mul_f32_e32 v254, v14, v96
	v_xor_b32_e32 v237, v238, v97
	v_mul_f32_e32 v250, v250, v237
	v_add_f32_e32 v250, v254, v250
	v_cndmask_b32_e64 v14, v14, v250, s[58:59]
	v_mul_f32_e32 v255, v15, v98
	v_xor_b32_e32 v237, v238, v99
	v_mul_f32_e32 v251, v251, v237
	v_add_f32_e32 v251, v255, v251
	v_cndmask_b32_e64 v15, v15, v251, s[58:59]
	v_mov_b64_e32 v[0:1], v[8:9]
	v_mov_b64_e32 v[2:3], v[10:11]
	v_mov_b64_e32 v[4:5], v[12:13]
	v_mov_b64_e32 v[6:7], v[14:15]
	s_and_b64 vcc, exec, s[8:9]
	s_mov_b64 s[58:59], -1
	s_cbranch_vccz .LBB0_662

;     DI void operator()(const pg8::f32x4 (&acc)[2][2][4][2], const pg8::Unit& u, int wr, int wc, int fr, int fq) const {
;     ...
;                     if (do_rope) {
;                         const f32x4* cs = (const f32x4*)(rope + (size_t)pos * 16);
;                         const f32x4 c01 = cs[0], c23 = cs[1], c45 = cs[2], c67 = cs[3];
;                         const float cc[8] = {c01.x, c01.z, c23.x, c23.z, c45.x, c45.z, c67.x, c67.z};
;                         const float sn[8] = {c01.y, c01.w, c23.y, c23.w, c45.y, c45.w, c67.y, c67.w};
; #pragma unroll
;                         for (int j = 0; j < 8; ++j) {
;                             const float other = __shfl_xor(v[j], 16);
;                             const float r0 = v[j] * cc[j] - other * sn[j], r1 = v[j] * cc[j] + other * sn[j];
;                             v[j] = fq == 0 ? r0 : (fq == 1 ? r1 : v[j]);
;                         }
;                     }
.LBB0_723:
	v_bitop3_b32 v104, s74, v181, v173 bitop3:0xc8
	v_lshlrev_b32_e32 v152, 6, v104
	v_lshl_add_u64 v[88:89], s[70:71], 0, v[152:153]
	s_andn2_b64 vcc, exec, s[58:59]
	v_lshl_add_u64 v[98:99], v[88:89], 0, s[34:35]
	s_cbranch_vccnz .LBB0_773
	global_load_dwordx4 v[92:95], v[98:99], off offset:16
	global_load_dwordx4 v[0:3], v[98:99], off
	global_load_dwordx4 v[88:91], v[98:99], off offset:48
	global_load_dwordx4 v[4:7], v[98:99], off offset:32
	v_and_b32_e32 v237, 1, v168
	v_cmp_eq_u32_e64 s[52:53], 1, v237
	v_cmp_gt_u32_e64 s[58:59], 2, v168
	v_cmp_eq_u32_e32 vcc, 0, v168
	v_bfrev_b32_e32 v239, 1
	v_cndmask_b32_e32 v238, 0, v239, vcc
	v_mov_b32_e32 v248, v8
	v_mov_b32_e32 v252, v8
	v_mov_b32_e32 v249, v9
	v_mov_b32_e32 v253, v9
	v_mov_b32_e32 v250, v10
	v_mov_b32_e32 v254, v10
	v_mov_b32_e32 v251, v11
	v_mov_b32_e32 v255, v11
	v_permlane16_swap_b32_e32 v248, v252
	v_permlane16_swap_b32_e32 v249, v253
	v_permlane16_swap_b32_e32 v250, v254
	v_permlane16_swap_b32_e32 v251, v255
	s_nop 1
	v_cndmask_b32_e64 v248, v252, v248, s[52:53]
	v_cndmask_b32_e64 v249, v253, v249, s[52:53]
	v_cndmask_b32_e64 v250, v254, v250, s[52:53]
	v_cndmask_b32_e64 v251, v255, v251, s[52:53]
	s_waitcnt vmcnt(0)
	v_mul_f32_e32 v252, v8, v0
	v_xor_b32_e32 v237, v238, v1
	v_mul_f32_e32 v248, v248, v237
	v_add_f32_e32 v248, v252, v248
	v_cndmask_b32_e64 v8, v8, v248, s[58:59]
	v_mul_f32_e32 v253, v9, v2
	v_xor_b32_e32 v237, v238, v3
	v_mul_f32_e32 v249, v249, v237
	v_add_f32_e32 v249, v253, v249
	v_cndmask_b32_e64 v9, v9, v249, s[58:59]
	v_mul_f32_e32 v254, v10, v92
	v_xor_b32_e32 v237, v238, v93
	v_mul_f32_e32 v250, v250, v237
	v_add_f32_e32 v250, v254, v250
	v_cndmask_b32_e64 v10, v10, v250, s[58:59]
	v_mul_f32_e32 v255, v11, v94
	v_xor_b32_e32 v237, v238, v95
	v_mul_f32_e32 v251, v251, v237
	v_add_f32_e32 v251, v255, v251
	v_cndmask_b32_e64 v11, v11, v251, s[58:59]
	v_mov_b32_e32 v248, v12
	v_mov_b32_e32 v252, v12
	v_mov_b32_e32 v249, v13
	v_mov_b32_e32 v253, v13
	v_mov_b32_e32 v250, v14
	v_mov_b32_e32 v254, v14
	v_mov_b32_e32 v251, v15
	v_mov_b32_e32 v255, v15
	v_permlane16_swap_b32_e32 v248, v252
	v_permlane16_swap_b32_e32 v249, v253
	v_permlane16_swap_b32_e32 v250, v254
	v_permlane16_swap_b32_e32 v251, v255
	s_nop 1
	v_cndmask_b32_e64 v248, v252, v248, s[52:53]
	v_cndmask_b32_e64 v249, v253, v249, s[52:53]
	v_cndmask_b32_e64 v250, v254, v250, s[52:53]
	v_cndmask_b32_e64 v251, v255, v251, s[52:53]
	v_mul_f32_e32 v252, v12, v4
	v_xor_b32_e32 v237, v238, v5
	v_mul_f32_e32 v248, v248, v237
	v_add_f32_e32 v248, v252, v248
	v_cndmask_b32_e64 v12, v12, v248, s[58:59]
	v_mul_f32_e32 v253, v13, v6
	v_xor_b32_e32 v237, v238, v7
	v_mul_f32_e32 v249, v249, v237
	v_add_f32_e32 v249, v253, v249
	v_cndmask_b32_e64 v13, v13, v249, s[58:59]
	v_mul_f32_e32 v254, v14, v88
	v_xor_b32_e32 v237, v238, v89
	v_mul_f32_e32 v250, v250, v237
	v_add_f32_e32 v250, v254, v250
	v_cndmask_b32_e64 v14, v14, v250, s[58:59]
	v_mul_f32_e32 v255, v15, v90
	v_xor_b32_e32 v237, v238, v91
	v_mul_f32_e32 v251, v251, v237
	v_add_f32_e32 v251, v255, v251
	v_cndmask_b32_e64 v15, v15, v251, s[58:59]
	v_mov_b64_e32 v[0:1], v[8:9]
	v_mov_b64_e32 v[2:3], v[10:11]
	v_mov_b64_e32 v[4:5], v[12:13]
	v_mov_b64_e32 v[6:7], v[14:15]

;     DI void operator()(const pg8::f32x4 (&acc)[2][2][4][2], const pg8::Unit& u, int wr, int wc, int fr, int fq) const {
;     ...
;                     if (do_rope) {
;                         const f32x4* cs = (const f32x4*)(rope + (size_t)pos * 16);
;                         const f32x4 c01 = cs[0], c23 = cs[1], c45 = cs[2], c67 = cs[3];
;                         const float cc[8] = {c01.x, c01.z, c23.x, c23.z, c45.x, c45.z, c67.x, c67.z};
;                         const float sn[8] = {c01.y, c01.w, c23.y, c23.w, c45.y, c45.w, c67.y, c67.w};
; #pragma unroll
;                         for (int j = 0; j < 8; ++j) {
;                             const float other = __shfl_xor(v[j], 16);
;                             const float r0 = v[j] * cc[j] - other * sn[j], r1 = v[j] * cc[j] + other * sn[j];
;                             v[j] = fq == 0 ? r0 : (fq == 1 ? r1 : v[j]);
;                         }
;                     }
.LBB0_814:
	global_load_dwordx4 v[84:87], v[98:99], off offset:16
	global_load_dwordx4 v[0:3], v[98:99], off
	global_load_dwordx4 v[80:83], v[98:99], off offset:48
	global_load_dwordx4 v[4:7], v[98:99], off offset:32
	v_and_b32_e32 v237, 1, v168
	v_cmp_eq_u32_e64 s[52:53], 1, v237
	v_cmp_gt_u32_e64 s[58:59], 2, v168
	v_cmp_eq_u32_e32 vcc, 0, v168
	v_bfrev_b32_e32 v239, 1
	v_cndmask_b32_e32 v238, 0, v239, vcc
	v_mov_b32_e32 v248, v8
	v_mov_b32_e32 v252, v8
	v_mov_b32_e32 v249, v9
	v_mov_b32_e32 v253, v9
	v_mov_b32_e32 v250, v10
	v_mov_b32_e32 v254, v10
	v_mov_b32_e32 v251, v11
	v_mov_b32_e32 v255, v11
	v_permlane16_swap_b32_e32 v248, v252
	v_permlane16_swap_b32_e32 v249, v253
	v_permlane16_swap_b32_e32 v250, v254
	v_permlane16_swap_b32_e32 v251, v255
	s_nop 1
	v_cndmask_b32_e64 v248, v252, v248, s[52:53]
	v_cndmask_b32_e64 v249, v253, v249, s[52:53]
	v_cndmask_b32_e64 v250, v254, v250, s[52:53]
	v_cndmask_b32_e64 v251, v255, v251, s[52:53]
	s_waitcnt vmcnt(0)
	v_mul_f32_e32 v252, v8, v0
	v_xor_b32_e32 v237, v238, v1
	v_mul_f32_e32 v248, v248, v237
	v_add_f32_e32 v248, v252, v248
	v_cndmask_b32_e64 v8, v8, v248, s[58:59]
	v_mul_f32_e32 v253, v9, v2
	v_xor_b32_e32 v237, v238, v3
	v_mul_f32_e32 v249, v249, v237
	v_add_f32_e32 v249, v253, v249
	v_cndmask_b32_e64 v9, v9, v249, s[58:59]
	v_mul_f32_e32 v254, v10, v84
	v_xor_b32_e32 v237, v238, v85
	v_mul_f32_e32 v250, v250, v237
	v_add_f32_e32 v250, v254, v250
	v_cndmask_b32_e64 v10, v10, v250, s[58:59]
	v_mul_f32_e32 v255, v11, v86
	v_xor_b32_e32 v237, v238, v87
	v_mul_f32_e32 v251, v251, v237
	v_add_f32_e32 v251, v255, v251
	v_cndmask_b32_e64 v11, v11, v251, s[58:59]
	v_mov_b32_e32 v248, v12
	v_mov_b32_e32 v252, v12
	v_mov_b32_e32 v249, v13
	v_mov_b32_e32 v253, v13
	v_mov_b32_e32 v250, v14
	v_mov_b32_e32 v254, v14
	v_mov_b32_e32 v251, v15
	v_mov_b32_e32 v255, v15
	v_permlane16_swap_b32_e32 v248, v252
	v_permlane16_swap_b32_e32 v249, v253
	v_permlane16_swap_b32_e32 v250, v254
	v_permlane16_swap_b32_e32 v251, v255
	s_nop 1
	v_cndmask_b32_e64 v248, v252, v248, s[52:53]
	v_cndmask_b32_e64 v249, v253, v249, s[52:53]
	v_cndmask_b32_e64 v250, v254, v250, s[52:53]
	v_cndmask_b32_e64 v251, v255, v251, s[52:53]
	v_mul_f32_e32 v252, v12, v4
	v_xor_b32_e32 v237, v238, v5
	v_mul_f32_e32 v248, v248, v237
	v_add_f32_e32 v248, v252, v248
	v_cndmask_b32_e64 v12, v12, v248, s[58:59]
	v_mul_f32_e32 v253, v13, v6
	v_xor_b32_e32 v237, v238, v7
	v_mul_f32_e32 v249, v249, v237
	v_add_f32_e32 v249, v253, v249
	v_cndmask_b32_e64 v13, v13, v249, s[58:59]
	v_mul_f32_e32 v254, v14, v80
	v_xor_b32_e32 v237, v238, v81
	v_mul_f32_e32 v250, v250, v237
	v_add_f32_e32 v250, v254, v250
	v_cndmask_b32_e64 v14, v14, v250, s[58:59]
	v_mul_f32_e32 v255, v15, v82
	v_xor_b32_e32 v237, v238, v83
	v_mul_f32_e32 v251, v251, v237
	v_add_f32_e32 v251, v255, v251
	v_cndmask_b32_e64 v15, v15, v251, s[58:59]
	v_mov_b64_e32 v[0:1], v[8:9]
	v_mov_b64_e32 v[2:3], v[10:11]
	v_mov_b64_e32 v[4:5], v[12:13]
	v_mov_b64_e32 v[6:7], v[14:15]
	s_and_b64 vcc, exec, s[8:9]
	s_mov_b64 s[58:59], -1
	s_cbranch_vccz .LBB0_806

;     DI void operator()(const pg8::f32x4 (&acc)[2][2][4][2], const pg8::Unit& u, int wr, int wc, int fr, int fq) const {
;     ...
;                     if (do_rope) {
;                         const f32x4* cs = (const f32x4*)(rope + (size_t)pos * 16);
;                         const f32x4 c01 = cs[0], c23 = cs[1], c45 = cs[2], c67 = cs[3];
;                         const float cc[8] = {c01.x, c01.z, c23.x, c23.z, c45.x, c45.z, c67.x, c67.z};
;                         const float sn[8] = {c01.y, c01.w, c23.y, c23.w, c45.y, c45.w, c67.y, c67.w};
; #pragma unroll
;                         for (int j = 0; j < 8; ++j) {
;                             const float other = __shfl_xor(v[j], 16);
;                             const float r0 = v[j] * cc[j] - other * sn[j], r1 = v[j] * cc[j] + other * sn[j];
;                             v[j] = fq == 0 ? r0 : (fq == 1 ? r1 : v[j]);
;                         }
;                     }
.LBB0_867:
	v_bitop3_b32 v88, s74, v177, v167 bitop3:0xc8
	v_lshlrev_b32_e32 v152, 6, v88
	v_lshl_add_u64 v[72:73], s[70:71], 0, v[152:153]
	s_andn2_b64 vcc, exec, s[58:59]
	v_lshl_add_u64 v[82:83], v[72:73], 0, s[34:35]
	s_cbranch_vccnz .LBB0_917
	global_load_dwordx4 v[76:79], v[82:83], off offset:16
	global_load_dwordx4 v[0:3], v[82:83], off
	global_load_dwordx4 v[72:75], v[82:83], off offset:48
	global_load_dwordx4 v[4:7], v[82:83], off offset:32
	v_and_b32_e32 v237, 1, v168
	v_cmp_eq_u32_e64 s[52:53], 1, v237
	v_cmp_gt_u32_e64 s[58:59], 2, v168
	v_cmp_eq_u32_e32 vcc, 0, v168
	v_bfrev_b32_e32 v239, 1
	v_cndmask_b32_e32 v238, 0, v239, vcc
	v_mov_b32_e32 v248, v8
	v_mov_b32_e32 v252, v8
	v_mov_b32_e32 v249, v9
	v_mov_b32_e32 v253, v9
	v_mov_b32_e32 v250, v10
	v_mov_b32_e32 v254, v10
	v_mov_b32_e32 v251, v11
	v_mov_b32_e32 v255, v11
	v_permlane16_swap_b32_e32 v248, v252
	v_permlane16_swap_b32_e32 v249, v253
	v_permlane16_swap_b32_e32 v250, v254
	v_permlane16_swap_b32_e32 v251, v255
	s_nop 1
	v_cndmask_b32_e64 v248, v252, v248, s[52:53]
	v_cndmask_b32_e64 v249, v253, v249, s[52:53]
	v_cndmask_b32_e64 v250, v254, v250, s[52:53]
	v_cndmask_b32_e64 v251, v255, v251, s[52:53]
	s_waitcnt vmcnt(0)
	v_mul_f32_e32 v252, v8, v0
	v_xor_b32_e32 v237, v238, v1
	v_mul_f32_e32 v248, v248, v237
	v_add_f32_e32 v248, v252, v248
	v_cndmask_b32_e64 v8, v8, v248, s[58:59]
	v_mul_f32_e32 v253, v9, v2
	v_xor_b32_e32 v237, v238, v3
	v_mul_f32_e32 v249, v249, v237
	v_add_f32_e32 v249, v253, v249
	v_cndmask_b32_e64 v9, v9, v249, s[58:59]
	v_mul_f32_e32 v254, v10, v76
	v_xor_b32_e32 v237, v238, v77
	v_mul_f32_e32 v250, v250, v237
	v_add_f32_e32 v250, v254, v250
	v_cndmask_b32_e64 v10, v10, v250, s[58:59]
	v_mul_f32_e32 v255, v11, v78
	v_xor_b32_e32 v237, v238, v79
	v_mul_f32_e32 v251, v251, v237
	v_add_f32_e32 v251, v255, v251
	v_cndmask_b32_e64 v11, v11, v251, s[58:59]
	v_mov_b32_e32 v248, v12
	v_mov_b32_e32 v252, v12
	v_mov_b32_e32 v249, v13
	v_mov_b32_e32 v253, v13
	v_mov_b32_e32 v250, v14
	v_mov_b32_e32 v254, v14
	v_mov_b32_e32 v251, v15
	v_mov_b32_e32 v255, v15
	v_permlane16_swap_b32_e32 v248, v252
	v_permlane16_swap_b32_e32 v249, v253
	v_permlane16_swap_b32_e32 v250, v254
	v_permlane16_swap_b32_e32 v251, v255
	s_nop 1
	v_cndmask_b32_e64 v248, v252, v248, s[52:53]
	v_cndmask_b32_e64 v249, v253, v249, s[52:53]
	v_cndmask_b32_e64 v250, v254, v250, s[52:53]
	v_cndmask_b32_e64 v251, v255, v251, s[52:53]
	v_mul_f32_e32 v252, v12, v4
	v_xor_b32_e32 v237, v238, v5
	v_mul_f32_e32 v248, v248, v237
	v_add_f32_e32 v248, v252, v248
	v_cndmask_b32_e64 v12, v12, v248, s[58:59]
	v_mul_f32_e32 v253, v13, v6
	v_xor_b32_e32 v237, v238, v7
	v_mul_f32_e32 v249, v249, v237
	v_add_f32_e32 v249, v253, v249
	v_cndmask_b32_e64 v13, v13, v249, s[58:59]
	v_mul_f32_e32 v254, v14, v72
	v_xor_b32_e32 v237, v238, v73
	v_mul_f32_e32 v250, v250, v237
	v_add_f32_e32 v250, v254, v250
	v_cndmask_b32_e64 v14, v14, v250, s[58:59]
	v_mul_f32_e32 v255, v15, v74
	v_xor_b32_e32 v237, v238, v75
	v_mul_f32_e32 v251, v251, v237
	v_add_f32_e32 v251, v255, v251
	v_cndmask_b32_e64 v15, v15, v251, s[58:59]
	v_mov_b64_e32 v[0:1], v[8:9]
	v_mov_b64_e32 v[2:3], v[10:11]
	v_mov_b64_e32 v[4:5], v[12:13]
	v_mov_b64_e32 v[6:7], v[14:15]

;     DI void operator()(const pg8::f32x4 (&acc)[2][2][4][2], const pg8::Unit& u, int wr, int wc, int fr, int fq) const {
;     ...
;                     if (do_rope) {
;                         const f32x4* cs = (const f32x4*)(rope + (size_t)pos * 16);
;                         const f32x4 c01 = cs[0], c23 = cs[1], c45 = cs[2], c67 = cs[3];
;                         const float cc[8] = {c01.x, c01.z, c23.x, c23.z, c45.x, c45.z, c67.x, c67.z};
;                         const float sn[8] = {c01.y, c01.w, c23.y, c23.w, c45.y, c45.w, c67.y, c67.w};
; #pragma unroll
;                         for (int j = 0; j < 8; ++j) {
;                             const float other = __shfl_xor(v[j], 16);
;                             const float r0 = v[j] * cc[j] - other * sn[j], r1 = v[j] * cc[j] + other * sn[j];
;                             v[j] = fq == 0 ? r0 : (fq == 1 ? r1 : v[j]);
;                         }
;                     }
.LBB0_958:
	global_load_dwordx4 v[68:71], v[82:83], off offset:16
	global_load_dwordx4 v[0:3], v[82:83], off
	global_load_dwordx4 v[64:67], v[82:83], off offset:48
	global_load_dwordx4 v[4:7], v[82:83], off offset:32
	v_and_b32_e32 v237, 1, v168
	v_cmp_eq_u32_e64 s[52:53], 1, v237
	v_cmp_gt_u32_e64 s[58:59], 2, v168
	v_cmp_eq_u32_e32 vcc, 0, v168
	v_bfrev_b32_e32 v239, 1
	v_cndmask_b32_e32 v238, 0, v239, vcc
	v_mov_b32_e32 v248, v8
	v_mov_b32_e32 v252, v8
	v_mov_b32_e32 v249, v9
	v_mov_b32_e32 v253, v9
	v_mov_b32_e32 v250, v10
	v_mov_b32_e32 v254, v10
	v_mov_b32_e32 v251, v11
	v_mov_b32_e32 v255, v11
	v_permlane16_swap_b32_e32 v248, v252
	v_permlane16_swap_b32_e32 v249, v253
	v_permlane16_swap_b32_e32 v250, v254
	v_permlane16_swap_b32_e32 v251, v255
	s_nop 1
	v_cndmask_b32_e64 v248, v252, v248, s[52:53]
	v_cndmask_b32_e64 v249, v253, v249, s[52:53]
	v_cndmask_b32_e64 v250, v254, v250, s[52:53]
	v_cndmask_b32_e64 v251, v255, v251, s[52:53]
	s_waitcnt vmcnt(0)
	v_mul_f32_e32 v252, v8, v0
	v_xor_b32_e32 v237, v238, v1
	v_mul_f32_e32 v248, v248, v237
	v_add_f32_e32 v248, v252, v248
	v_cndmask_b32_e64 v8, v8, v248, s[58:59]
	v_mul_f32_e32 v253, v9, v2
	v_xor_b32_e32 v237, v238, v3
	v_mul_f32_e32 v249, v249, v237
	v_add_f32_e32 v249, v253, v249
	v_cndmask_b32_e64 v9, v9, v249, s[58:59]
	v_mul_f32_e32 v254, v10, v68
	v_xor_b32_e32 v237, v238, v69
	v_mul_f32_e32 v250, v250, v237
	v_add_f32_e32 v250, v254, v250
	v_cndmask_b32_e64 v10, v10, v250, s[58:59]
	v_mul_f32_e32 v255, v11, v70
	v_xor_b32_e32 v237, v238, v71
	v_mul_f32_e32 v251, v251, v237
	v_add_f32_e32 v251, v255, v251
	v_cndmask_b32_e64 v11, v11, v251, s[58:59]
	v_mov_b32_e32 v248, v12
	v_mov_b32_e32 v252, v12
	v_mov_b32_e32 v249, v13
	v_mov_b32_e32 v253, v13
	v_mov_b32_e32 v250, v14
	v_mov_b32_e32 v254, v14
	v_mov_b32_e32 v251, v15
	v_mov_b32_e32 v255, v15
	v_permlane16_swap_b32_e32 v248, v252
	v_permlane16_swap_b32_e32 v249, v253
	v_permlane16_swap_b32_e32 v250, v254
	v_permlane16_swap_b32_e32 v251, v255
	s_nop 1
	v_cndmask_b32_e64 v248, v252, v248, s[52:53]
	v_cndmask_b32_e64 v249, v253, v249, s[52:53]
	v_cndmask_b32_e64 v250, v254, v250, s[52:53]
	v_cndmask_b32_e64 v251, v255, v251, s[52:53]
	v_mul_f32_e32 v252, v12, v4
	v_xor_b32_e32 v237, v238, v5
	v_mul_f32_e32 v248, v248, v237
	v_add_f32_e32 v248, v252, v248
	v_cndmask_b32_e64 v12, v12, v248, s[58:59]
	v_mul_f32_e32 v253, v13, v6
	v_xor_b32_e32 v237, v238, v7
	v_mul_f32_e32 v249, v249, v237
	v_add_f32_e32 v249, v253, v249
	v_cndmask_b32_e64 v13, v13, v249, s[58:59]
	v_mul_f32_e32 v254, v14, v64
	v_xor_b32_e32 v237, v238, v65
	v_mul_f32_e32 v250, v250, v237
	v_add_f32_e32 v250, v254, v250
	v_cndmask_b32_e64 v14, v14, v250, s[58:59]
	v_mul_f32_e32 v255, v15, v66
	v_xor_b32_e32 v237, v238, v67
	v_mul_f32_e32 v251, v251, v237
	v_add_f32_e32 v251, v255, v251
	v_cndmask_b32_e64 v15, v15, v251, s[58:59]
	v_mov_b64_e32 v[0:1], v[8:9]
	v_mov_b64_e32 v[2:3], v[10:11]
	v_mov_b64_e32 v[4:5], v[12:13]
	v_mov_b64_e32 v[6:7], v[14:15]
	s_and_b64 vcc, exec, s[8:9]
	s_mov_b64 s[58:59], -1
	s_cbranch_vccz .LBB0_950

;     DI void operator()(const pg8::f32x4 (&acc)[2][2][4][2], const pg8::Unit& u, int wr, int wc, int fr, int fq) const {
;     ...
;                     if (do_rope) {
;                         const f32x4* cs = (const f32x4*)(rope + (size_t)pos * 16);
;                         const f32x4 c01 = cs[0], c23 = cs[1], c45 = cs[2], c67 = cs[3];
;                         const float cc[8] = {c01.x, c01.z, c23.x, c23.z, c45.x, c45.z, c67.x, c67.z};
;                         const float sn[8] = {c01.y, c01.w, c23.y, c23.w, c45.y, c45.w, c67.y, c67.w};
; #pragma unroll
;                         for (int j = 0; j < 8; ++j) {
;                             const float other = __shfl_xor(v[j], 16);
;                             const float r0 = v[j] * cc[j] - other * sn[j], r1 = v[j] * cc[j] + other * sn[j];
;                             v[j] = fq == 0 ? r0 : (fq == 1 ? r1 : v[j]);
;                         }
;                     }
.LBB0_1011:
	v_bitop3_b32 v72, s74, v179, v171 bitop3:0xc8
	v_lshlrev_b32_e32 v152, 6, v72
	v_lshl_add_u64 v[56:57], s[70:71], 0, v[152:153]
	s_andn2_b64 vcc, exec, s[58:59]
	v_lshl_add_u64 v[66:67], v[56:57], 0, s[34:35]
	s_cbranch_vccnz .LBB0_1061
	global_load_dwordx4 v[60:63], v[66:67], off offset:16
	global_load_dwordx4 v[0:3], v[66:67], off
	global_load_dwordx4 v[56:59], v[66:67], off offset:48
	global_load_dwordx4 v[4:7], v[66:67], off offset:32
	v_and_b32_e32 v237, 1, v168
	v_cmp_eq_u32_e64 s[52:53], 1, v237
	v_cmp_gt_u32_e64 s[58:59], 2, v168
	v_cmp_eq_u32_e32 vcc, 0, v168
	v_bfrev_b32_e32 v239, 1
	v_cndmask_b32_e32 v238, 0, v239, vcc
	v_mov_b32_e32 v248, v8
	v_mov_b32_e32 v252, v8
	v_mov_b32_e32 v249, v9
	v_mov_b32_e32 v253, v9
	v_mov_b32_e32 v250, v10
	v_mov_b32_e32 v254, v10
	v_mov_b32_e32 v251, v11
	v_mov_b32_e32 v255, v11
	v_permlane16_swap_b32_e32 v248, v252
	v_permlane16_swap_b32_e32 v249, v253
	v_permlane16_swap_b32_e32 v250, v254
	v_permlane16_swap_b32_e32 v251, v255
	s_nop 1
	v_cndmask_b32_e64 v248, v252, v248, s[52:53]
	v_cndmask_b32_e64 v249, v253, v249, s[52:53]
	v_cndmask_b32_e64 v250, v254, v250, s[52:53]
	v_cndmask_b32_e64 v251, v255, v251, s[52:53]
	s_waitcnt vmcnt(0)
	v_mul_f32_e32 v252, v8, v0
	v_xor_b32_e32 v237, v238, v1
	v_mul_f32_e32 v248, v248, v237
	v_add_f32_e32 v248, v252, v248
	v_cndmask_b32_e64 v8, v8, v248, s[58:59]
	v_mul_f32_e32 v253, v9, v2
	v_xor_b32_e32 v237, v238, v3
	v_mul_f32_e32 v249, v249, v237
	v_add_f32_e32 v249, v253, v249
	v_cndmask_b32_e64 v9, v9, v249, s[58:59]
	v_mul_f32_e32 v254, v10, v60
	v_xor_b32_e32 v237, v238, v61
	v_mul_f32_e32 v250, v250, v237
	v_add_f32_e32 v250, v254, v250
	v_cndmask_b32_e64 v10, v10, v250, s[58:59]
	v_mul_f32_e32 v255, v11, v62
	v_xor_b32_e32 v237, v238, v63
	v_mul_f32_e32 v251, v251, v237
	v_add_f32_e32 v251, v255, v251
	v_cndmask_b32_e64 v11, v11, v251, s[58:59]
	v_mov_b32_e32 v248, v12
	v_mov_b32_e32 v252, v12
	v_mov_b32_e32 v249, v13
	v_mov_b32_e32 v253, v13
	v_mov_b32_e32 v250, v14
	v_mov_b32_e32 v254, v14
	v_mov_b32_e32 v251, v15
	v_mov_b32_e32 v255, v15
	v_permlane16_swap_b32_e32 v248, v252
	v_permlane16_swap_b32_e32 v249, v253
	v_permlane16_swap_b32_e32 v250, v254
	v_permlane16_swap_b32_e32 v251, v255
	s_nop 1
	v_cndmask_b32_e64 v248, v252, v248, s[52:53]
	v_cndmask_b32_e64 v249, v253, v249, s[52:53]
	v_cndmask_b32_e64 v250, v254, v250, s[52:53]
	v_cndmask_b32_e64 v251, v255, v251, s[52:53]
	v_mul_f32_e32 v252, v12, v4
	v_xor_b32_e32 v237, v238, v5
	v_mul_f32_e32 v248, v248, v237
	v_add_f32_e32 v248, v252, v248
	v_cndmask_b32_e64 v12, v12, v248, s[58:59]
	v_mul_f32_e32 v253, v13, v6
	v_xor_b32_e32 v237, v238, v7
	v_mul_f32_e32 v249, v249, v237
	v_add_f32_e32 v249, v253, v249
	v_cndmask_b32_e64 v13, v13, v249, s[58:59]
	v_mul_f32_e32 v254, v14, v56
	v_xor_b32_e32 v237, v238, v57
	v_mul_f32_e32 v250, v250, v237
	v_add_f32_e32 v250, v254, v250
	v_cndmask_b32_e64 v14, v14, v250, s[58:59]
	v_mul_f32_e32 v255, v15, v58
	v_xor_b32_e32 v237, v238, v59
	v_mul_f32_e32 v251, v251, v237
	v_add_f32_e32 v251, v255, v251
	v_cndmask_b32_e64 v15, v15, v251, s[58:59]
	v_mov_b64_e32 v[0:1], v[8:9]
	v_mov_b64_e32 v[2:3], v[10:11]
	v_mov_b64_e32 v[4:5], v[12:13]
	v_mov_b64_e32 v[6:7], v[14:15]

;     DI void operator()(const pg8::f32x4 (&acc)[2][2][4][2], const pg8::Unit& u, int wr, int wc, int fr, int fq) const {
;     ...
;                     if (do_rope) {
;                         const f32x4* cs = (const f32x4*)(rope + (size_t)pos * 16);
;                         const f32x4 c01 = cs[0], c23 = cs[1], c45 = cs[2], c67 = cs[3];
;                         const float cc[8] = {c01.x, c01.z, c23.x, c23.z, c45.x, c45.z, c67.x, c67.z};
;                         const float sn[8] = {c01.y, c01.w, c23.y, c23.w, c45.y, c45.w, c67.y, c67.w};
; #pragma unroll
;                         for (int j = 0; j < 8; ++j) {
;                             const float other = __shfl_xor(v[j], 16);
;                             const float r0 = v[j] * cc[j] - other * sn[j], r1 = v[j] * cc[j] + other * sn[j];
;                             v[j] = fq == 0 ? r0 : (fq == 1 ? r1 : v[j]);
;                         }
;                     }
.LBB0_1102:
	global_load_dwordx4 v[52:55], v[66:67], off offset:16
	global_load_dwordx4 v[0:3], v[66:67], off
	global_load_dwordx4 v[48:51], v[66:67], off offset:48
	global_load_dwordx4 v[4:7], v[66:67], off offset:32
	v_and_b32_e32 v237, 1, v168
	v_cmp_eq_u32_e64 s[52:53], 1, v237
	v_cmp_gt_u32_e64 s[58:59], 2, v168
	v_cmp_eq_u32_e32 vcc, 0, v168
	v_bfrev_b32_e32 v239, 1
	v_cndmask_b32_e32 v238, 0, v239, vcc
	v_mov_b32_e32 v248, v8
	v_mov_b32_e32 v252, v8
	v_mov_b32_e32 v249, v9
	v_mov_b32_e32 v253, v9
	v_mov_b32_e32 v250, v10
	v_mov_b32_e32 v254, v10
	v_mov_b32_e32 v251, v11
	v_mov_b32_e32 v255, v11
	v_permlane16_swap_b32_e32 v248, v252
	v_permlane16_swap_b32_e32 v249, v253
	v_permlane16_swap_b32_e32 v250, v254
	v_permlane16_swap_b32_e32 v251, v255
	s_nop 1
	v_cndmask_b32_e64 v248, v252, v248, s[52:53]
	v_cndmask_b32_e64 v249, v253, v249, s[52:53]
	v_cndmask_b32_e64 v250, v254, v250, s[52:53]
	v_cndmask_b32_e64 v251, v255, v251, s[52:53]
	s_waitcnt vmcnt(0)
	v_mul_f32_e32 v252, v8, v0
	v_xor_b32_e32 v237, v238, v1
	v_mul_f32_e32 v248, v248, v237
	v_add_f32_e32 v248, v252, v248
	v_cndmask_b32_e64 v8, v8, v248, s[58:59]
	v_mul_f32_e32 v253, v9, v2
	v_xor_b32_e32 v237, v238, v3
	v_mul_f32_e32 v249, v249, v237
	v_add_f32_e32 v249, v253, v249
	v_cndmask_b32_e64 v9, v9, v249, s[58:59]
	v_mul_f32_e32 v254, v10, v52
	v_xor_b32_e32 v237, v238, v53
	v_mul_f32_e32 v250, v250, v237
	v_add_f32_e32 v250, v254, v250
	v_cndmask_b32_e64 v10, v10, v250, s[58:59]
	v_mul_f32_e32 v255, v11, v54
	v_xor_b32_e32 v237, v238, v55
	v_mul_f32_e32 v251, v251, v237
	v_add_f32_e32 v251, v255, v251
	v_cndmask_b32_e64 v11, v11, v251, s[58:59]
	v_mov_b32_e32 v248, v12
	v_mov_b32_e32 v252, v12
	v_mov_b32_e32 v249, v13
	v_mov_b32_e32 v253, v13
	v_mov_b32_e32 v250, v14
	v_mov_b32_e32 v254, v14
	v_mov_b32_e32 v251, v15
	v_mov_b32_e32 v255, v15
	v_permlane16_swap_b32_e32 v248, v252
	v_permlane16_swap_b32_e32 v249, v253
	v_permlane16_swap_b32_e32 v250, v254
	v_permlane16_swap_b32_e32 v251, v255
	s_nop 1
	v_cndmask_b32_e64 v248, v252, v248, s[52:53]
	v_cndmask_b32_e64 v249, v253, v249, s[52:53]
	v_cndmask_b32_e64 v250, v254, v250, s[52:53]
	v_cndmask_b32_e64 v251, v255, v251, s[52:53]
	v_mul_f32_e32 v252, v12, v4
	v_xor_b32_e32 v237, v238, v5
	v_mul_f32_e32 v248, v248, v237
	v_add_f32_e32 v248, v252, v248
	v_cndmask_b32_e64 v12, v12, v248, s[58:59]
	v_mul_f32_e32 v253, v13, v6
	v_xor_b32_e32 v237, v238, v7
	v_mul_f32_e32 v249, v249, v237
	v_add_f32_e32 v249, v253, v249
	v_cndmask_b32_e64 v13, v13, v249, s[58:59]
	v_mul_f32_e32 v254, v14, v48
	v_xor_b32_e32 v237, v238, v49
	v_mul_f32_e32 v250, v250, v237
	v_add_f32_e32 v250, v254, v250
	v_cndmask_b32_e64 v14, v14, v250, s[58:59]
	v_mul_f32_e32 v255, v15, v50
	v_xor_b32_e32 v237, v238, v51
	v_mul_f32_e32 v251, v251, v237
	v_add_f32_e32 v251, v255, v251
	v_cndmask_b32_e64 v15, v15, v251, s[58:59]
	v_mov_b64_e32 v[0:1], v[8:9]
	v_mov_b64_e32 v[2:3], v[10:11]
	v_mov_b64_e32 v[4:5], v[12:13]
	v_mov_b64_e32 v[6:7], v[14:15]
	s_and_b64 vcc, exec, s[8:9]
	s_mov_b64 s[58:59], -1
	s_cbranch_vccz .LBB0_1094

;     DI void operator()(const pg8::f32x4 (&acc)[2][2][4][2], const pg8::Unit& u, int wr, int wc, int fr, int fq) const {
;     ...
;                     if (do_rope) {
;                         const f32x4* cs = (const f32x4*)(rope + (size_t)pos * 16);
;                         const f32x4 c01 = cs[0], c23 = cs[1], c45 = cs[2], c67 = cs[3];
;                         const float cc[8] = {c01.x, c01.z, c23.x, c23.z, c45.x, c45.z, c67.x, c67.z};
;                         const float sn[8] = {c01.y, c01.w, c23.y, c23.w, c45.y, c45.w, c67.y, c67.w};
; #pragma unroll
;                         for (int j = 0; j < 8; ++j) {
;                             const float other = __shfl_xor(v[j], 16);
;                             const float r0 = v[j] * cc[j] - other * sn[j], r1 = v[j] * cc[j] + other * sn[j];
;                             v[j] = fq == 0 ? r0 : (fq == 1 ? r1 : v[j]);
;                         }
;                     }
.LBB0_1155:
	v_bitop3_b32 v56, s74, v180, v172 bitop3:0xc8
	v_lshlrev_b32_e32 v152, 6, v56
	v_lshl_add_u64 v[40:41], s[70:71], 0, v[152:153]
	s_andn2_b64 vcc, exec, s[58:59]
	v_lshl_add_u64 v[50:51], v[40:41], 0, s[34:35]
	s_cbranch_vccnz .LBB0_1205
	global_load_dwordx4 v[44:47], v[50:51], off offset:16
	global_load_dwordx4 v[0:3], v[50:51], off
	global_load_dwordx4 v[40:43], v[50:51], off offset:48
	global_load_dwordx4 v[4:7], v[50:51], off offset:32
	v_and_b32_e32 v237, 1, v168
	v_cmp_eq_u32_e64 s[52:53], 1, v237
	v_cmp_gt_u32_e64 s[58:59], 2, v168
	v_cmp_eq_u32_e32 vcc, 0, v168
	v_bfrev_b32_e32 v239, 1
	v_cndmask_b32_e32 v238, 0, v239, vcc
	v_mov_b32_e32 v248, v8
	v_mov_b32_e32 v252, v8
	v_mov_b32_e32 v249, v9
	v_mov_b32_e32 v253, v9
	v_mov_b32_e32 v250, v10
	v_mov_b32_e32 v254, v10
	v_mov_b32_e32 v251, v11
	v_mov_b32_e32 v255, v11
	v_permlane16_swap_b32_e32 v248, v252
	v_permlane16_swap_b32_e32 v249, v253
	v_permlane16_swap_b32_e32 v250, v254
	v_permlane16_swap_b32_e32 v251, v255
	s_nop 1
	v_cndmask_b32_e64 v248, v252, v248, s[52:53]
	v_cndmask_b32_e64 v249, v253, v249, s[52:53]
	v_cndmask_b32_e64 v250, v254, v250, s[52:53]
	v_cndmask_b32_e64 v251, v255, v251, s[52:53]
	s_waitcnt vmcnt(0)
	v_mul_f32_e32 v252, v8, v0
	v_xor_b32_e32 v237, v238, v1
	v_mul_f32_e32 v248, v248, v237
	v_add_f32_e32 v248, v252, v248
	v_cndmask_b32_e64 v8, v8, v248, s[58:59]
	v_mul_f32_e32 v253, v9, v2
	v_xor_b32_e32 v237, v238, v3
	v_mul_f32_e32 v249, v249, v237
	v_add_f32_e32 v249, v253, v249
	v_cndmask_b32_e64 v9, v9, v249, s[58:59]
	v_mul_f32_e32 v254, v10, v44
	v_xor_b32_e32 v237, v238, v45
	v_mul_f32_e32 v250, v250, v237
	v_add_f32_e32 v250, v254, v250
	v_cndmask_b32_e64 v10, v10, v250, s[58:59]
	v_mul_f32_e32 v255, v11, v46
	v_xor_b32_e32 v237, v238, v47
	v_mul_f32_e32 v251, v251, v237
	v_add_f32_e32 v251, v255, v251
	v_cndmask_b32_e64 v11, v11, v251, s[58:59]
	v_mov_b32_e32 v248, v12
	v_mov_b32_e32 v252, v12
	v_mov_b32_e32 v249, v13
	v_mov_b32_e32 v253, v13
	v_mov_b32_e32 v250, v14
	v_mov_b32_e32 v254, v14
	v_mov_b32_e32 v251, v15
	v_mov_b32_e32 v255, v15
	v_permlane16_swap_b32_e32 v248, v252
	v_permlane16_swap_b32_e32 v249, v253
	v_permlane16_swap_b32_e32 v250, v254
	v_permlane16_swap_b32_e32 v251, v255
	s_nop 1
	v_cndmask_b32_e64 v248, v252, v248, s[52:53]
	v_cndmask_b32_e64 v249, v253, v249, s[52:53]
	v_cndmask_b32_e64 v250, v254, v250, s[52:53]
	v_cndmask_b32_e64 v251, v255, v251, s[52:53]
	v_mul_f32_e32 v252, v12, v4
	v_xor_b32_e32 v237, v238, v5
	v_mul_f32_e32 v248, v248, v237
	v_add_f32_e32 v248, v252, v248
	v_cndmask_b32_e64 v12, v12, v248, s[58:59]
	v_mul_f32_e32 v253, v13, v6
	v_xor_b32_e32 v237, v238, v7
	v_mul_f32_e32 v249, v249, v237
	v_add_f32_e32 v249, v253, v249
	v_cndmask_b32_e64 v13, v13, v249, s[58:59]
	v_mul_f32_e32 v254, v14, v40
	v_xor_b32_e32 v237, v238, v41
	v_mul_f32_e32 v250, v250, v237
	v_add_f32_e32 v250, v254, v250
	v_cndmask_b32_e64 v14, v14, v250, s[58:59]
	v_mul_f32_e32 v255, v15, v42
	v_xor_b32_e32 v237, v238, v43
	v_mul_f32_e32 v251, v251, v237
	v_add_f32_e32 v251, v255, v251
	v_cndmask_b32_e64 v15, v15, v251, s[58:59]
	v_mov_b64_e32 v[0:1], v[8:9]
	v_mov_b64_e32 v[2:3], v[10:11]
	v_mov_b64_e32 v[4:5], v[12:13]
	v_mov_b64_e32 v[6:7], v[14:15]

;     DI void operator()(const pg8::f32x4 (&acc)[2][2][4][2], const pg8::Unit& u, int wr, int wc, int fr, int fq) const {
;     ...
;                     if (do_rope) {
;                         const f32x4* cs = (const f32x4*)(rope + (size_t)pos * 16);
;                         const f32x4 c01 = cs[0], c23 = cs[1], c45 = cs[2], c67 = cs[3];
;                         const float cc[8] = {c01.x, c01.z, c23.x, c23.z, c45.x, c45.z, c67.x, c67.z};
;                         const float sn[8] = {c01.y, c01.w, c23.y, c23.w, c45.y, c45.w, c67.y, c67.w};
; #pragma unroll
;                         for (int j = 0; j < 8; ++j) {
;                             const float other = __shfl_xor(v[j], 16);
;                             const float r0 = v[j] * cc[j] - other * sn[j], r1 = v[j] * cc[j] + other * sn[j];
;                             v[j] = fq == 0 ? r0 : (fq == 1 ? r1 : v[j]);
;                         }
;                     }
.LBB0_1246:
	global_load_dwordx4 v[36:39], v[50:51], off offset:16
	global_load_dwordx4 v[0:3], v[50:51], off
	global_load_dwordx4 v[32:35], v[50:51], off offset:48
	global_load_dwordx4 v[4:7], v[50:51], off offset:32
	v_and_b32_e32 v237, 1, v168
	v_cmp_eq_u32_e64 s[52:53], 1, v237
	v_cmp_gt_u32_e64 s[58:59], 2, v168
	v_cmp_eq_u32_e32 vcc, 0, v168
	v_bfrev_b32_e32 v239, 1
	v_cndmask_b32_e32 v238, 0, v239, vcc
	v_mov_b32_e32 v248, v8
	v_mov_b32_e32 v252, v8
	v_mov_b32_e32 v249, v9
	v_mov_b32_e32 v253, v9
	v_mov_b32_e32 v250, v10
	v_mov_b32_e32 v254, v10
	v_mov_b32_e32 v251, v11
	v_mov_b32_e32 v255, v11
	v_permlane16_swap_b32_e32 v248, v252
	v_permlane16_swap_b32_e32 v249, v253
	v_permlane16_swap_b32_e32 v250, v254
	v_permlane16_swap_b32_e32 v251, v255
	s_nop 1
	v_cndmask_b32_e64 v248, v252, v248, s[52:53]
	v_cndmask_b32_e64 v249, v253, v249, s[52:53]
	v_cndmask_b32_e64 v250, v254, v250, s[52:53]
	v_cndmask_b32_e64 v251, v255, v251, s[52:53]
	s_waitcnt vmcnt(0)
	v_mul_f32_e32 v252, v8, v0
	v_xor_b32_e32 v237, v238, v1
	v_mul_f32_e32 v248, v248, v237
	v_add_f32_e32 v248, v252, v248
	v_cndmask_b32_e64 v8, v8, v248, s[58:59]
	v_mul_f32_e32 v253, v9, v2
	v_xor_b32_e32 v237, v238, v3
	v_mul_f32_e32 v249, v249, v237
	v_add_f32_e32 v249, v253, v249
	v_cndmask_b32_e64 v9, v9, v249, s[58:59]
	v_mul_f32_e32 v254, v10, v36
	v_xor_b32_e32 v237, v238, v37
	v_mul_f32_e32 v250, v250, v237
	v_add_f32_e32 v250, v254, v250
	v_cndmask_b32_e64 v10, v10, v250, s[58:59]
	v_mul_f32_e32 v255, v11, v38
	v_xor_b32_e32 v237, v238, v39
	v_mul_f32_e32 v251, v251, v237
	v_add_f32_e32 v251, v255, v251
	v_cndmask_b32_e64 v11, v11, v251, s[58:59]
	v_mov_b32_e32 v248, v12
	v_mov_b32_e32 v252, v12
	v_mov_b32_e32 v249, v13
	v_mov_b32_e32 v253, v13
	v_mov_b32_e32 v250, v14
	v_mov_b32_e32 v254, v14
	v_mov_b32_e32 v251, v15
	v_mov_b32_e32 v255, v15
	v_permlane16_swap_b32_e32 v248, v252
	v_permlane16_swap_b32_e32 v249, v253
	v_permlane16_swap_b32_e32 v250, v254
	v_permlane16_swap_b32_e32 v251, v255
	s_nop 1
	v_cndmask_b32_e64 v248, v252, v248, s[52:53]
	v_cndmask_b32_e64 v249, v253, v249, s[52:53]
	v_cndmask_b32_e64 v250, v254, v250, s[52:53]
	v_cndmask_b32_e64 v251, v255, v251, s[52:53]
	v_mul_f32_e32 v252, v12, v4
	v_xor_b32_e32 v237, v238, v5
	v_mul_f32_e32 v248, v248, v237
	v_add_f32_e32 v248, v252, v248
	v_cndmask_b32_e64 v12, v12, v248, s[58:59]
	v_mul_f32_e32 v253, v13, v6
	v_xor_b32_e32 v237, v238, v7
	v_mul_f32_e32 v249, v249, v237
	v_add_f32_e32 v249, v253, v249
	v_cndmask_b32_e64 v13, v13, v249, s[58:59]
	v_mul_f32_e32 v254, v14, v32
	v_xor_b32_e32 v237, v238, v33
	v_mul_f32_e32 v250, v250, v237
	v_add_f32_e32 v250, v254, v250
	v_cndmask_b32_e64 v14, v14, v250, s[58:59]
	v_mul_f32_e32 v255, v15, v34
	v_xor_b32_e32 v237, v238, v35
	v_mul_f32_e32 v251, v251, v237
	v_add_f32_e32 v251, v255, v251
	v_cndmask_b32_e64 v15, v15, v251, s[58:59]
	v_mov_b64_e32 v[0:1], v[8:9]
	v_mov_b64_e32 v[2:3], v[10:11]
	v_mov_b64_e32 v[4:5], v[12:13]
	v_mov_b64_e32 v[6:7], v[14:15]
	s_and_b64 vcc, exec, s[8:9]
	s_mov_b64 s[58:59], -1
	s_cbranch_vccz .LBB0_1238

;     DI void operator()(const pg8::f32x4 (&acc)[2][2][4][2], const pg8::Unit& u, int wr, int wc, int fr, int fq) const {
;     ...
;                     if (do_rope) {
;                         const f32x4* cs = (const f32x4*)(rope + (size_t)pos * 16);
;                         const f32x4 c01 = cs[0], c23 = cs[1], c45 = cs[2], c67 = cs[3];
;                         const float cc[8] = {c01.x, c01.z, c23.x, c23.z, c45.x, c45.z, c67.x, c67.z};
;                         const float sn[8] = {c01.y, c01.w, c23.y, c23.w, c45.y, c45.w, c67.y, c67.w};
; #pragma unroll
;                         for (int j = 0; j < 8; ++j) {
;                             const float other = __shfl_xor(v[j], 16);
;                             const float r0 = v[j] * cc[j] - other * sn[j], r1 = v[j] * cc[j] + other * sn[j];
;                             v[j] = fq == 0 ? r0 : (fq == 1 ? r1 : v[j]);
;                         }
;                     }
.LBB0_1299:
	v_bitop3_b32 v40, s74, v181, v173 bitop3:0xc8
	v_lshlrev_b32_e32 v152, 6, v40
	v_lshl_add_u64 v[24:25], s[70:71], 0, v[152:153]
	s_andn2_b64 vcc, exec, s[10:11]
	v_lshl_add_u64 v[34:35], v[24:25], 0, s[34:35]
	s_cbranch_vccnz .LBB0_1349
	global_load_dwordx4 v[28:31], v[34:35], off offset:16
	global_load_dwordx4 v[0:3], v[34:35], off
	global_load_dwordx4 v[24:27], v[34:35], off offset:48
	global_load_dwordx4 v[4:7], v[34:35], off offset:32
	v_and_b32_e32 v237, 1, v168
	v_cmp_eq_u32_e64 s[10:11], 1, v237
	v_cmp_gt_u32_e64 s[58:59], 2, v168
	v_cmp_eq_u32_e32 vcc, 0, v168
	v_bfrev_b32_e32 v239, 1
	v_cndmask_b32_e32 v238, 0, v239, vcc
	v_mov_b32_e32 v248, v8
	v_mov_b32_e32 v252, v8
	v_mov_b32_e32 v249, v9
	v_mov_b32_e32 v253, v9
	v_mov_b32_e32 v250, v10
	v_mov_b32_e32 v254, v10
	v_mov_b32_e32 v251, v11
	v_mov_b32_e32 v255, v11
	v_permlane16_swap_b32_e32 v248, v252
	v_permlane16_swap_b32_e32 v249, v253
	v_permlane16_swap_b32_e32 v250, v254
	v_permlane16_swap_b32_e32 v251, v255
	s_nop 1
	v_cndmask_b32_e64 v248, v252, v248, s[10:11]
	v_cndmask_b32_e64 v249, v253, v249, s[10:11]
	v_cndmask_b32_e64 v250, v254, v250, s[10:11]
	v_cndmask_b32_e64 v251, v255, v251, s[10:11]
	s_waitcnt vmcnt(0)
	v_mul_f32_e32 v252, v8, v0
	v_xor_b32_e32 v237, v238, v1
	v_mul_f32_e32 v248, v248, v237
	v_add_f32_e32 v248, v252, v248
	v_cndmask_b32_e64 v8, v8, v248, s[58:59]
	v_mul_f32_e32 v253, v9, v2
	v_xor_b32_e32 v237, v238, v3
	v_mul_f32_e32 v249, v249, v237
	v_add_f32_e32 v249, v253, v249
	v_cndmask_b32_e64 v9, v9, v249, s[58:59]
	v_mul_f32_e32 v254, v10, v28
	v_xor_b32_e32 v237, v238, v29
	v_mul_f32_e32 v250, v250, v237
	v_add_f32_e32 v250, v254, v250
	v_cndmask_b32_e64 v10, v10, v250, s[58:59]
	v_mul_f32_e32 v255, v11, v30
	v_xor_b32_e32 v237, v238, v31
	v_mul_f32_e32 v251, v251, v237
	v_add_f32_e32 v251, v255, v251
	v_cndmask_b32_e64 v11, v11, v251, s[58:59]
	v_mov_b32_e32 v248, v12
	v_mov_b32_e32 v252, v12
	v_mov_b32_e32 v249, v13
	v_mov_b32_e32 v253, v13
	v_mov_b32_e32 v250, v14
	v_mov_b32_e32 v254, v14
	v_mov_b32_e32 v251, v15
	v_mov_b32_e32 v255, v15
	v_permlane16_swap_b32_e32 v248, v252
	v_permlane16_swap_b32_e32 v249, v253
	v_permlane16_swap_b32_e32 v250, v254
	v_permlane16_swap_b32_e32 v251, v255
	s_nop 1
	v_cndmask_b32_e64 v248, v252, v248, s[10:11]
	v_cndmask_b32_e64 v249, v253, v249, s[10:11]
	v_cndmask_b32_e64 v250, v254, v250, s[10:11]
	v_cndmask_b32_e64 v251, v255, v251, s[10:11]
	v_mul_f32_e32 v252, v12, v4
	v_xor_b32_e32 v237, v238, v5
	v_mul_f32_e32 v248, v248, v237
	v_add_f32_e32 v248, v252, v248
	v_cndmask_b32_e64 v12, v12, v248, s[58:59]
	v_mul_f32_e32 v253, v13, v6
	v_xor_b32_e32 v237, v238, v7
	v_mul_f32_e32 v249, v249, v237
	v_add_f32_e32 v249, v253, v249
	v_cndmask_b32_e64 v13, v13, v249, s[58:59]
	v_mul_f32_e32 v254, v14, v24
	v_xor_b32_e32 v237, v238, v25
	v_mul_f32_e32 v250, v250, v237
	v_add_f32_e32 v250, v254, v250
	v_cndmask_b32_e64 v14, v14, v250, s[58:59]
	v_mul_f32_e32 v255, v15, v26
	v_xor_b32_e32 v237, v238, v27
	v_mul_f32_e32 v251, v251, v237
	v_add_f32_e32 v251, v255, v251
	v_cndmask_b32_e64 v15, v15, v251, s[58:59]
	v_mov_b64_e32 v[0:1], v[8:9]
	v_mov_b64_e32 v[2:3], v[10:11]
	v_mov_b64_e32 v[4:5], v[12:13]
	v_mov_b64_e32 v[6:7], v[14:15]

;     DI void operator()(const pg8::f32x4 (&acc)[2][2][4][2], const pg8::Unit& u, int wr, int wc, int fr, int fq) const {
;     ...
;                     if (do_rope) {
;                         const f32x4* cs = (const f32x4*)(rope + (size_t)pos * 16);
;                         const f32x4 c01 = cs[0], c23 = cs[1], c45 = cs[2], c67 = cs[3];
;                         const float cc[8] = {c01.x, c01.z, c23.x, c23.z, c45.x, c45.z, c67.x, c67.z};
;                         const float sn[8] = {c01.y, c01.w, c23.y, c23.w, c45.y, c45.w, c67.y, c67.w};
; #pragma unroll
;                         for (int j = 0; j < 8; ++j) {
;                             const float other = __shfl_xor(v[j], 16);
;                             const float r0 = v[j] * cc[j] - other * sn[j], r1 = v[j] * cc[j] + other * sn[j];
;                             v[j] = fq == 0 ? r0 : (fq == 1 ? r1 : v[j]);
;                         }
;                     }
.LBB0_1390:
	global_load_dwordx4 v[20:23], v[34:35], off offset:16
	global_load_dwordx4 v[0:3], v[34:35], off
	global_load_dwordx4 v[16:19], v[34:35], off offset:48
	global_load_dwordx4 v[4:7], v[34:35], off offset:32
	v_and_b32_e32 v237, 1, v168
	v_cmp_eq_u32_e64 s[6:7], 1, v237
	v_cmp_gt_u32_e64 s[10:11], 2, v168
	v_cmp_eq_u32_e32 vcc, 0, v168
	v_bfrev_b32_e32 v239, 1
	v_cndmask_b32_e32 v238, 0, v239, vcc
	v_mov_b32_e32 v248, v8
	v_mov_b32_e32 v252, v8
	v_mov_b32_e32 v249, v9
	v_mov_b32_e32 v253, v9
	v_mov_b32_e32 v250, v10
	v_mov_b32_e32 v254, v10
	v_mov_b32_e32 v251, v11
	v_mov_b32_e32 v255, v11
	v_permlane16_swap_b32_e32 v248, v252
	v_permlane16_swap_b32_e32 v249, v253
	v_permlane16_swap_b32_e32 v250, v254
	v_permlane16_swap_b32_e32 v251, v255
	s_nop 1
	v_cndmask_b32_e64 v248, v252, v248, s[6:7]
	v_cndmask_b32_e64 v249, v253, v249, s[6:7]
	v_cndmask_b32_e64 v250, v254, v250, s[6:7]
	v_cndmask_b32_e64 v251, v255, v251, s[6:7]
	s_waitcnt vmcnt(0)
	v_mul_f32_e32 v252, v8, v0
	v_xor_b32_e32 v237, v238, v1
	v_mul_f32_e32 v248, v248, v237
	v_add_f32_e32 v248, v252, v248
	v_cndmask_b32_e64 v8, v8, v248, s[10:11]
	v_mul_f32_e32 v253, v9, v2
	v_xor_b32_e32 v237, v238, v3
	v_mul_f32_e32 v249, v249, v237
	v_add_f32_e32 v249, v253, v249
	v_cndmask_b32_e64 v9, v9, v249, s[10:11]
	v_mul_f32_e32 v254, v10, v20
	v_xor_b32_e32 v237, v238, v21
	v_mul_f32_e32 v250, v250, v237
	v_add_f32_e32 v250, v254, v250
	v_cndmask_b32_e64 v10, v10, v250, s[10:11]
	v_mul_f32_e32 v255, v11, v22
	v_xor_b32_e32 v237, v238, v23
	v_mul_f32_e32 v251, v251, v237
	v_add_f32_e32 v251, v255, v251
	v_cndmask_b32_e64 v11, v11, v251, s[10:11]
	v_mov_b32_e32 v248, v12
	v_mov_b32_e32 v252, v12
	v_mov_b32_e32 v249, v13
	v_mov_b32_e32 v253, v13
	v_mov_b32_e32 v250, v14
	v_mov_b32_e32 v254, v14
	v_mov_b32_e32 v251, v15
	v_mov_b32_e32 v255, v15
	v_permlane16_swap_b32_e32 v248, v252
	v_permlane16_swap_b32_e32 v249, v253
	v_permlane16_swap_b32_e32 v250, v254
	v_permlane16_swap_b32_e32 v251, v255
	s_nop 1
	v_cndmask_b32_e64 v248, v252, v248, s[6:7]
	v_cndmask_b32_e64 v249, v253, v249, s[6:7]
	v_cndmask_b32_e64 v250, v254, v250, s[6:7]
	v_cndmask_b32_e64 v251, v255, v251, s[6:7]
	v_mul_f32_e32 v252, v12, v4
	v_xor_b32_e32 v237, v238, v5
	v_mul_f32_e32 v248, v248, v237
	v_add_f32_e32 v248, v252, v248
	v_cndmask_b32_e64 v12, v12, v248, s[10:11]
	v_mul_f32_e32 v253, v13, v6
	v_xor_b32_e32 v237, v238, v7
	v_mul_f32_e32 v249, v249, v237
	v_add_f32_e32 v249, v253, v249
	v_cndmask_b32_e64 v13, v13, v249, s[10:11]
	v_mul_f32_e32 v254, v14, v16
	v_xor_b32_e32 v237, v238, v17
	v_mul_f32_e32 v250, v250, v237
	v_add_f32_e32 v250, v254, v250
	v_cndmask_b32_e64 v14, v14, v250, s[10:11]
	v_mul_f32_e32 v255, v15, v18
	v_xor_b32_e32 v237, v238, v19
	v_mul_f32_e32 v251, v251, v237
	v_add_f32_e32 v251, v255, v251
	v_cndmask_b32_e64 v15, v15, v251, s[10:11]
	v_mov_b64_e32 v[0:1], v[8:9]
	v_mov_b64_e32 v[2:3], v[10:11]
	v_mov_b64_e32 v[4:5], v[12:13]
	v_mov_b64_e32 v[6:7], v[14:15]
	s_and_b64 vcc, exec, s[8:9]
	s_mov_b64 s[6:7], -1
	s_cbranch_vccz .LBB0_1382
